# GEMM out-projection epilogue hand-written: gate and x loads of all 64 accumulator elements issued together, one wait, fmac, stores (was load-wait-store per element); RWKV prologue weight loads batched
# speedup vs baseline: 1.2417x; 1.0203x over previous
.LBB0_250:
	s_cmp_gt_i32 s81, 10
	s_mov_b64 s[4:5], -1
	s_cbranch_scc0 .LBB0_688
	s_mov_b32 s82, s2
	s_cmpk_gt_i32 s82, 0x7f
	s_cbranch_scc0 .LBB0_545
	s_cmpk_gt_u32 s82, 0xff
	s_cbranch_scc1 .LBB0_544
	s_and_b32 s32, s82, 1
	s_sub_i32 s82, s82, 0x80
	s_lshr_b32 s82, s82, 1
	s_add_i32 s82, s82, 0x80
	s_add_i32 s22, s82, 0xffffff80
	s_mov_b64 s[18:19], s[84:85]
	v_readlane_b32 s4, v255, 17
	v_mov_b32_e32 v116, v119
	s_lshr_b32 s36, s22, 5
	s_and_b32 s4, s4, 6
	s_waitcnt lgkmcnt(0)
	s_load_dwordx2 s[20:21], s[18:19], 0x120
	s_or_b32 s14, s36, s4
	s_load_dwordx2 s[10:11], s[18:19], 0x58
	s_load_dwordx2 s[12:13], s[18:19], 0x68
	s_load_dwordx4 s[4:7], s[18:19], 0x78
	s_load_dwordx2 s[16:17], s[18:19], 0x88
	s_bfe_u32 s35, s82, 0x30002
	v_readlane_b32 s9, v255, 18
	s_lshl_b32 s8, s14, 9
	s_lshl_b32 s34, s35, 6
	s_lshl_b32 s9, s9, 11
	s_waitcnt lgkmcnt(0)
	s_add_u32 s23, s4, s9
	s_addc_u32 s24, s5, 0
	s_add_u32 s25, s6, s9
	s_addc_u32 s26, s7, 0
	s_add_u32 s4, s16, s9
	s_movk_i32 s9, 0x80
	s_addc_u32 s5, s17, 0
	v_cmp_gt_u32_e64 s[16:17], s9, v116
	s_waitcnt vmcnt(0)
	v_mov_b32_e32 v0, 0x70
	v_mov_b32_e32 v1, 0x60
	v_cndmask_b32_e64 v16, v0, v1, s[16:17]
	v_lshl_add_u64 v[0:1], s[18:19], 0, v[16:17]
	global_load_dwordx2 v[0:1], v[0:1], off
	s_lshl_b32 s52, s35, 8
	v_bfe_u32 v139, v116, 4, 2
	s_add_u32 s6, s4, s52
	s_mov_b32 s15, s53
	v_and_b32_e32 v140, 15, v116
	s_addc_u32 s7, s5, 0
	s_lshl_b64 s[14:15], s[14:15], 17
	v_lshlrev_b32_e32 v20, 12, v139
	v_or_b32_e32 v2, v20, v140
	v_lshlrev_b32_e32 v16, 2, v2
	v_or_b32_e32 v19, 0x400, v20
	v_or_b32_e32 v18, 0x600, v20
	v_or_b32_e32 v15, 0x800, v20
	v_or_b32_e32 v14, 0xa00, v20
	v_or_b32_e32 v13, 0xc00, v20
	v_or_b32_e32 v12, 0xe00, v20
	v_or_b32_e32 v6, 0x4000, v20
	v_or_b32_e32 v11, 0x4200, v20
	v_or_b32_e32 v10, 0x4400, v20
	v_or_b32_e32 v9, 0x4600, v20
	v_or_b32_e32 v8, 0x4800, v20
	v_or_b32_e32 v7, 0x4a00, v20
	v_or_b32_e32 v21, 16, v140
	s_and_b32 s38, s82, 3
	s_mov_b32 s9, s53
	v_lshlrev_b32_e32 v122, 2, v140
	v_mov_b32_e32 v123, v17
	s_movk_i32 s4, 0x7f
	v_cmp_lt_u32_e64 s[4:5], s4, v116
	s_waitcnt vmcnt(0)
	v_lshl_add_u64 v[0:1], v[0:1], 0, s[14:15]
	v_lshl_add_u64 v[0:1], v[0:1], 0, s[52:53]
	v_lshl_add_u64 v[2:3], v[0:1], 0, v[16:17]
	global_load_dword v141, v[2:3], off
	s_nop 0
	s_nop 0
	global_load_dword v142, v[2:3], off offset:2048
	s_nop 0
	s_nop 0
	v_or_b32_e32 v4, v19, v140
	v_lshlrev_b32_e32 v16, 2, v4
	v_lshl_add_u64 v[4:5], v[0:1], 0, v[16:17]
	global_load_dword v143, v[4:5], off
	s_nop 0
	s_nop 0
	v_or_b32_e32 v4, v18, v140
	v_lshlrev_b32_e32 v16, 2, v4
	v_lshl_add_u64 v[4:5], v[0:1], 0, v[16:17]
	global_load_dword v145, v[4:5], off
	s_nop 0
	s_nop 0
	v_or_b32_e32 v4, v15, v140
	v_lshlrev_b32_e32 v16, 2, v4
	v_lshl_add_u64 v[4:5], v[0:1], 0, v[16:17]
	global_load_dword v147, v[4:5], off
	s_nop 0
	s_nop 0
	v_or_b32_e32 v4, v14, v140
	v_lshlrev_b32_e32 v16, 2, v4
	v_lshl_add_u64 v[4:5], v[0:1], 0, v[16:17]
	global_load_dword v149, v[4:5], off
	s_nop 0
	s_nop 0
	v_or_b32_e32 v4, v13, v140
	v_lshlrev_b32_e32 v16, 2, v4
	v_lshl_add_u64 v[4:5], v[0:1], 0, v[16:17]
	global_load_dword v151, v[4:5], off
	s_nop 0
	s_nop 0
	v_or_b32_e32 v4, v12, v140
	v_lshlrev_b32_e32 v16, 2, v4
	v_lshl_add_u64 v[4:5], v[0:1], 0, v[16:17]
	global_load_dword v153, v[4:5], off
	s_nop 0
	s_nop 0
	v_or_b32_e32 v4, v6, v140
	v_lshlrev_b32_e32 v16, 2, v4
	v_lshl_add_u64 v[4:5], v[0:1], 0, v[16:17]
	global_load_dword v144, v[4:5], off
	s_nop 0
	s_nop 0
	v_or_b32_e32 v4, v11, v140
	v_lshlrev_b32_e32 v16, 2, v4
	v_lshl_add_u64 v[4:5], v[0:1], 0, v[16:17]
	global_load_dword v146, v[4:5], off
	s_nop 0
	s_nop 0
	v_or_b32_e32 v4, v10, v140
	v_lshlrev_b32_e32 v16, 2, v4
	v_lshl_add_u64 v[4:5], v[0:1], 0, v[16:17]
	global_load_dword v148, v[4:5], off
	s_nop 0
	s_nop 0
	v_or_b32_e32 v4, v9, v140
	v_lshlrev_b32_e32 v16, 2, v4
	v_lshl_add_u64 v[4:5], v[0:1], 0, v[16:17]
	global_load_dword v150, v[4:5], off
	s_nop 0
	s_nop 0
	v_or_b32_e32 v4, v8, v140
	v_lshlrev_b32_e32 v16, 2, v4
	v_lshl_add_u64 v[4:5], v[0:1], 0, v[16:17]
	global_load_dword v152, v[4:5], off
	s_nop 0
	s_nop 0
	v_or_b32_e32 v4, v7, v140
	v_lshlrev_b32_e32 v16, 2, v4
	v_lshl_add_u64 v[4:5], v[0:1], 0, v[16:17]
	global_load_dword v4, v[4:5], off
	v_or_b32_e32 v5, 0x4c00, v20
	s_waitcnt vmcnt(0)
	v_cvt_pk_bf16_f32 v154, v4, v17
	v_or_b32_e32 v4, v5, v140
	v_lshlrev_b32_e32 v16, 2, v4
	v_lshl_add_u64 v[22:23], v[0:1], 0, v[16:17]
	global_load_dword v4, v[22:23], off
	s_waitcnt vmcnt(0)
	v_cvt_pk_bf16_f32 v155, v4, v17
	v_or_b32_e32 v4, 0x4e00, v20
	v_or_b32_e32 v16, v4, v140
	v_lshlrev_b32_e32 v16, 2, v16
	v_lshl_add_u64 v[22:23], v[0:1], 0, v[16:17]
	global_load_dword v156, v[22:23], off
	s_nop 0
	s_nop 0
	global_load_dword v157, v[2:3], off offset:64
	s_nop 0
	s_nop 0
	v_or_b32_e32 v16, v20, v21
	v_lshlrev_b32_e32 v16, 2, v16
	v_lshl_add_u64 v[22:23], v[0:1], 0, v[16:17]
	global_load_dword v158, v[22:23], off offset:2048
	s_nop 0
	s_nop 0
	v_or_b32_e32 v16, v19, v21
	v_lshlrev_b32_e32 v16, 2, v16
	v_lshl_add_u64 v[22:23], v[0:1], 0, v[16:17]
	global_load_dword v159, v[22:23], off
	s_nop 0
	s_nop 0
	v_or_b32_e32 v16, v18, v21
	v_lshlrev_b32_e32 v16, 2, v16
	v_lshl_add_u64 v[22:23], v[0:1], 0, v[16:17]
	global_load_dword v160, v[22:23], off
	s_nop 0
	s_nop 0
	v_or_b32_e32 v16, v15, v21
	v_lshlrev_b32_e32 v16, 2, v16
	v_lshl_add_u64 v[22:23], v[0:1], 0, v[16:17]
	global_load_dword v161, v[22:23], off
	s_nop 0
	s_nop 0
	v_or_b32_e32 v16, v14, v21
	v_lshlrev_b32_e32 v16, 2, v16
	v_lshl_add_u64 v[22:23], v[0:1], 0, v[16:17]
	global_load_dword v162, v[22:23], off
	s_nop 0
	s_nop 0
	v_or_b32_e32 v16, v13, v21
	v_lshlrev_b32_e32 v16, 2, v16
	v_lshl_add_u64 v[22:23], v[0:1], 0, v[16:17]
	global_load_dword v163, v[22:23], off
	s_nop 0
	s_nop 0
	v_or_b32_e32 v16, v12, v21
	v_lshlrev_b32_e32 v16, 2, v16
	v_lshl_add_u64 v[22:23], v[0:1], 0, v[16:17]
	global_load_dword v165, v[22:23], off
	s_nop 0
	s_nop 0
	v_or_b32_e32 v16, v6, v21
	v_lshlrev_b32_e32 v16, 2, v16
	v_lshl_add_u64 v[22:23], v[0:1], 0, v[16:17]
	global_load_dword v164, v[22:23], off
	s_nop 0
	s_nop 0
	v_or_b32_e32 v16, v11, v21
	v_lshlrev_b32_e32 v16, 2, v16
	v_lshl_add_u64 v[22:23], v[0:1], 0, v[16:17]
	global_load_dword v166, v[22:23], off
	s_nop 0
	s_nop 0
	v_or_b32_e32 v16, v10, v21
	v_lshlrev_b32_e32 v16, 2, v16
	v_lshl_add_u64 v[22:23], v[0:1], 0, v[16:17]
	global_load_dword v167, v[22:23], off
	s_nop 0
	s_nop 0
	v_or_b32_e32 v16, v9, v21
	v_lshlrev_b32_e32 v16, 2, v16
	v_lshl_add_u64 v[22:23], v[0:1], 0, v[16:17]
	global_load_dword v168, v[22:23], off
	s_nop 0
	s_nop 0
	v_or_b32_e32 v16, v8, v21
	v_lshlrev_b32_e32 v16, 2, v16
	v_lshl_add_u64 v[22:23], v[0:1], 0, v[16:17]
	global_load_dword v169, v[22:23], off
	s_nop 0
	s_nop 0
	v_or_b32_e32 v16, v7, v21
	v_lshlrev_b32_e32 v16, 2, v16
	v_lshl_add_u64 v[22:23], v[0:1], 0, v[16:17]
	global_load_dword v170, v[22:23], off
	s_nop 0
	s_nop 0
	v_or_b32_e32 v16, v5, v21
	v_lshlrev_b32_e32 v16, 2, v16
	v_lshl_add_u64 v[22:23], v[0:1], 0, v[16:17]
	global_load_dword v171, v[22:23], off
	s_nop 0
	s_nop 0
	v_or_b32_e32 v16, v4, v21
	v_lshlrev_b32_e32 v16, 2, v16
	v_lshl_add_u64 v[22:23], v[0:1], 0, v[16:17]
	global_load_dword v172, v[22:23], off
	s_nop 0
	s_nop 0
	v_or_b32_e32 v21, 32, v140
	global_load_dword v173, v[2:3], off offset:128
	s_nop 0
	s_nop 0
	v_or_b32_e32 v16, v20, v21
	v_lshlrev_b32_e32 v16, 2, v16
	v_lshl_add_u64 v[22:23], v[0:1], 0, v[16:17]
	global_load_dword v174, v[22:23], off offset:2048
	s_nop 0
	s_nop 0
	v_or_b32_e32 v16, v19, v21
	v_lshlrev_b32_e32 v16, 2, v16
	v_lshl_add_u64 v[22:23], v[0:1], 0, v[16:17]
	global_load_dword v16, v[22:23], off
	s_add_u32 s14, s25, s52
	global_load_dword v2, v[2:3], off offset:192
	s_waitcnt vmcnt(1)
	v_cvt_pk_bf16_f32 v176, v16, v17
	v_or_b32_e32 v16, v18, v21
	v_lshlrev_b32_e32 v16, 2, v16
	v_lshl_add_u64 v[22:23], v[0:1], 0, v[16:17]
	global_load_dword v16, v[22:23], off
	s_waitcnt vmcnt(0)
	v_cvt_pk_bf16_f32 v178, v16, v17
	v_or_b32_e32 v16, v15, v21
	v_lshlrev_b32_e32 v16, 2, v16
	v_lshl_add_u64 v[22:23], v[0:1], 0, v[16:17]
	global_load_dword v180, v[22:23], off
	s_nop 0
	s_nop 0
	v_or_b32_e32 v16, v14, v21
	v_lshlrev_b32_e32 v16, 2, v16
	v_lshl_add_u64 v[22:23], v[0:1], 0, v[16:17]
	global_load_dword v182, v[22:23], off
	s_nop 0
	s_nop 0
	v_or_b32_e32 v16, v13, v21
	v_lshlrev_b32_e32 v16, 2, v16
	v_lshl_add_u64 v[22:23], v[0:1], 0, v[16:17]
	global_load_dword v184, v[22:23], off
	s_nop 0
	s_nop 0
	v_or_b32_e32 v16, v12, v21
	v_lshlrev_b32_e32 v16, 2, v16
	v_lshl_add_u64 v[22:23], v[0:1], 0, v[16:17]
	global_load_dword v186, v[22:23], off
	s_nop 0
	s_nop 0
	v_or_b32_e32 v16, v6, v21
	v_lshlrev_b32_e32 v16, 2, v16
	v_lshl_add_u64 v[22:23], v[0:1], 0, v[16:17]
	global_load_dword v175, v[22:23], off
	s_nop 0
	s_nop 0
	v_or_b32_e32 v16, v11, v21
	v_lshlrev_b32_e32 v16, 2, v16
	v_lshl_add_u64 v[22:23], v[0:1], 0, v[16:17]
	global_load_dword v177, v[22:23], off
	s_nop 0
	s_nop 0
	v_or_b32_e32 v16, v10, v21
	v_lshlrev_b32_e32 v16, 2, v16
	v_lshl_add_u64 v[22:23], v[0:1], 0, v[16:17]
	global_load_dword v179, v[22:23], off
	s_nop 0
	s_nop 0
	v_or_b32_e32 v16, v9, v21
	v_lshlrev_b32_e32 v16, 2, v16
	v_lshl_add_u64 v[22:23], v[0:1], 0, v[16:17]
	global_load_dword v181, v[22:23], off
	s_nop 0
	s_nop 0
	v_or_b32_e32 v16, v8, v21
	v_lshlrev_b32_e32 v16, 2, v16
	v_lshl_add_u64 v[22:23], v[0:1], 0, v[16:17]
	global_load_dword v183, v[22:23], off
	s_nop 0
	s_nop 0
	v_or_b32_e32 v16, v7, v21
	v_lshlrev_b32_e32 v16, 2, v16
	v_lshl_add_u64 v[22:23], v[0:1], 0, v[16:17]
	global_load_dword v185, v[22:23], off
	s_nop 0
	s_nop 0
	v_or_b32_e32 v16, v5, v21
	v_lshlrev_b32_e32 v16, 2, v16
	v_lshl_add_u64 v[22:23], v[0:1], 0, v[16:17]
	global_load_dword v187, v[22:23], off
	s_nop 0
	s_nop 0
	v_or_b32_e32 v16, v4, v21
	v_lshlrev_b32_e32 v16, 2, v16
	v_lshl_add_u64 v[22:23], v[0:1], 0, v[16:17]
	v_or_b32_e32 v21, 48, v140
	global_load_dword v16, v[22:23], off
	v_cvt_pk_bf16_f32 v189, v2, v17
	v_or_b32_e32 v2, v20, v21
	s_waitcnt vmcnt(0)
	v_cvt_pk_bf16_f32 v188, v16, v17
	v_lshlrev_b32_e32 v16, 2, v2
	v_lshl_add_u64 v[2:3], v[0:1], 0, v[16:17]
	global_load_dword v2, v[2:3], off offset:2048
	s_waitcnt vmcnt(0)
	v_cvt_pk_bf16_f32 v190, v2, v17
	v_or_b32_e32 v2, v19, v21
	v_lshlrev_b32_e32 v16, 2, v2
	v_lshl_add_u64 v[2:3], v[0:1], 0, v[16:17]
	global_load_dword v191, v[2:3], off
	s_nop 0
	s_nop 0
	v_or_b32_e32 v2, v18, v21
	v_lshlrev_b32_e32 v16, 2, v2
	v_lshl_add_u64 v[2:3], v[0:1], 0, v[16:17]
	global_load_dword v192, v[2:3], off
	s_nop 0
	s_nop 0
	v_or_b32_e32 v2, v15, v21
	v_lshlrev_b32_e32 v16, 2, v2
	v_lshl_add_u64 v[2:3], v[0:1], 0, v[16:17]
	global_load_dword v193, v[2:3], off
	s_nop 0
	s_nop 0
	v_or_b32_e32 v2, v14, v21
	v_lshlrev_b32_e32 v16, 2, v2
	v_lshl_add_u64 v[2:3], v[0:1], 0, v[16:17]
	global_load_dword v194, v[2:3], off
	s_nop 0
	s_nop 0
	v_or_b32_e32 v2, v13, v21
	v_lshlrev_b32_e32 v16, 2, v2
	v_lshl_add_u64 v[2:3], v[0:1], 0, v[16:17]
	global_load_dword v195, v[2:3], off
	s_nop 0
	s_nop 0
	v_or_b32_e32 v2, v12, v21
	v_lshlrev_b32_e32 v16, 2, v2
	v_lshl_add_u64 v[2:3], v[0:1], 0, v[16:17]
	global_load_dword v198, v[2:3], off
	s_nop 0
	s_nop 0
	v_or_b32_e32 v2, v6, v21
	v_lshlrev_b32_e32 v16, 2, v2
	v_lshl_add_u64 v[2:3], v[0:1], 0, v[16:17]
	global_load_dword v196, v[2:3], off
	s_nop 0
	s_nop 0
	v_or_b32_e32 v2, v11, v21
	v_lshlrev_b32_e32 v16, 2, v2
	v_lshl_add_u64 v[2:3], v[0:1], 0, v[16:17]
	global_load_dword v197, v[2:3], off
	s_nop 0
	s_nop 0
	v_or_b32_e32 v2, v10, v21
	v_lshlrev_b32_e32 v16, 2, v2
	v_lshl_add_u64 v[2:3], v[0:1], 0, v[16:17]
	global_load_dword v199, v[2:3], off
	s_nop 0
	s_nop 0
	v_or_b32_e32 v2, v9, v21
	v_lshlrev_b32_e32 v16, 2, v2
	v_lshl_add_u64 v[2:3], v[0:1], 0, v[16:17]
	global_load_dword v200, v[2:3], off
	s_nop 0
	s_nop 0
	v_or_b32_e32 v2, v8, v21
	v_lshlrev_b32_e32 v16, 2, v2
	v_lshl_add_u64 v[2:3], v[0:1], 0, v[16:17]
	global_load_dword v201, v[2:3], off
	s_nop 0
	s_nop 0
	v_or_b32_e32 v2, v7, v21
	v_lshlrev_b32_e32 v16, 2, v2
	v_lshl_add_u64 v[2:3], v[0:1], 0, v[16:17]
	global_load_dword v202, v[2:3], off
	s_nop 0
	s_nop 0
	v_or_b32_e32 v2, v5, v21
	v_lshlrev_b32_e32 v16, 2, v2
	v_lshl_add_u64 v[2:3], v[0:1], 0, v[16:17]
	global_load_dword v203, v[2:3], off
	s_nop 0
	s_nop 0
	v_or_b32_e32 v2, v4, v21
	v_lshlrev_b32_e32 v16, 2, v2
	v_lshl_add_u64 v[0:1], v[0:1], 0, v[16:17]
	global_load_dword v204, v[0:1], off
	s_nop 0
	s_nop 0
	s_waitcnt vmcnt(0)
	v_cvt_pk_bf16_f32 v141, v141, v17
	v_cvt_pk_bf16_f32 v142, v142, v17
	v_cvt_pk_bf16_f32 v143, v143, v17
	v_cvt_pk_bf16_f32 v145, v145, v17
	v_cvt_pk_bf16_f32 v147, v147, v17
	v_cvt_pk_bf16_f32 v149, v149, v17
	v_cvt_pk_bf16_f32 v151, v151, v17
	v_cvt_pk_bf16_f32 v153, v153, v17
	v_cvt_pk_bf16_f32 v144, v144, v17
	v_cvt_pk_bf16_f32 v146, v146, v17
	v_cvt_pk_bf16_f32 v148, v148, v17
	v_cvt_pk_bf16_f32 v150, v150, v17
	v_cvt_pk_bf16_f32 v152, v152, v17
	v_cvt_pk_bf16_f32 v156, v156, v17
	v_cvt_pk_bf16_f32 v157, v157, v17
	v_cvt_pk_bf16_f32 v158, v158, v17
	v_cvt_pk_bf16_f32 v159, v159, v17
	v_cvt_pk_bf16_f32 v160, v160, v17
	v_cvt_pk_bf16_f32 v161, v161, v17
	v_cvt_pk_bf16_f32 v162, v162, v17
	v_cvt_pk_bf16_f32 v163, v163, v17
	v_cvt_pk_bf16_f32 v165, v165, v17
	v_cvt_pk_bf16_f32 v164, v164, v17
	v_cvt_pk_bf16_f32 v166, v166, v17
	v_cvt_pk_bf16_f32 v167, v167, v17
	v_cvt_pk_bf16_f32 v168, v168, v17
	v_cvt_pk_bf16_f32 v169, v169, v17
	v_cvt_pk_bf16_f32 v170, v170, v17
	v_cvt_pk_bf16_f32 v171, v171, v17
	v_cvt_pk_bf16_f32 v172, v172, v17
	v_cvt_pk_bf16_f32 v173, v173, v17
	v_cvt_pk_bf16_f32 v174, v174, v17
	v_cvt_pk_bf16_f32 v180, v180, v17
	v_cvt_pk_bf16_f32 v182, v182, v17
	v_cvt_pk_bf16_f32 v184, v184, v17
	v_cvt_pk_bf16_f32 v186, v186, v17
	v_cvt_pk_bf16_f32 v175, v175, v17
	v_cvt_pk_bf16_f32 v177, v177, v17
	v_cvt_pk_bf16_f32 v179, v179, v17
	v_cvt_pk_bf16_f32 v181, v181, v17
	v_cvt_pk_bf16_f32 v183, v183, v17
	v_cvt_pk_bf16_f32 v185, v185, v17
	v_cvt_pk_bf16_f32 v187, v187, v17
	v_cvt_pk_bf16_f32 v191, v191, v17
	v_cvt_pk_bf16_f32 v192, v192, v17
	v_cvt_pk_bf16_f32 v193, v193, v17
	v_cvt_pk_bf16_f32 v194, v194, v17
	v_cvt_pk_bf16_f32 v195, v195, v17
	v_cvt_pk_bf16_f32 v198, v198, v17
	v_cvt_pk_bf16_f32 v196, v196, v17
	v_cvt_pk_bf16_f32 v197, v197, v17
	v_cvt_pk_bf16_f32 v199, v199, v17
	v_cvt_pk_bf16_f32 v200, v200, v17
	v_cvt_pk_bf16_f32 v201, v201, v17
	v_cvt_pk_bf16_f32 v202, v202, v17
	v_cvt_pk_bf16_f32 v203, v203, v17
	v_cvt_pk_bf16_f32 v204, v204, v17
	v_mov_b32_e32 v0, s13
	v_mov_b32_e32 v1, s11
	s_addc_u32 s15, s26, 0
	s_lshl_b32 s37, s38, 4
	v_cndmask_b32_e64 v1, v0, v1, s[16:17]
	v_mov_b32_e32 v0, s12
	v_mov_b32_e32 v2, s10
	v_cndmask_b32_e64 v0, v0, v2, s[16:17]
	s_add_u32 s58, s20, 0x6aa8000
	v_lshl_add_u64 v[0:1], s[8:9], 2, v[0:1]
	s_addc_u32 s59, s21, 0
	v_lshl_add_u64 v[0:1], v[0:1], 0, s[52:53]
	s_add_u32 s8, s23, s52
	v_lshl_add_u64 v[0:1], v[0:1], 0, v[122:123]
	s_addc_u32 s9, s24, 0
	global_load_dword v117, v[0:1], off
	global_load_dword v121, v[0:1], off offset:64
	global_load_dword v123, v[0:1], off offset:128
	global_load_dword v125, v[0:1], off offset:192
	global_load_dword v127, v122, s[8:9]
	global_load_dword v128, v122, s[14:15]
	global_load_dword v129, v122, s[6:7]
	global_load_dword v130, v122, s[8:9] offset:64
	global_load_dword v131, v122, s[14:15] offset:64
	global_load_dword v132, v122, s[6:7] offset:64
	global_load_dword v133, v122, s[8:9] offset:128
	global_load_dword v134, v122, s[14:15] offset:128
	global_load_dword v135, v122, s[6:7] offset:128
	global_load_dword v136, v122, s[8:9] offset:192
	global_load_dword v137, v122, s[14:15] offset:192
	global_load_dword v138, v122, s[6:7] offset:192
	s_or_b32 s40, s34, s37
	s_cmp_gt_u32 s22, 31
	s_cselect_b64 s[62:63], -1, 0
	s_cmp_lt_u32 s22, 32
	s_cselect_b64 s[64:65], -1, 0
	s_and_b64 s[6:7], s[64:65], exec
	s_cselect_b32 s43, 0, 0xe0
	s_lshl_b32 s6, s36, 6
	s_mov_b32 s8, 0x78787879
	s_add_i32 s41, s6, 0x5c0
	s_or_b32 s39, s6, 0x580
	s_movk_i32 s6, 0x440
	v_mov_b32_e32 v23, 0
	v_mul_hi_i32 v0, v116, s8
	s_addk_i32 s40, 0x300
	s_add_i32 s42, s34, 0x1c0
	v_cmp_gt_i32_e64 s[6:7], s6, v116
	v_lshrrev_b32_e32 v205, 31, v0
	v_ashrrev_i32_e32 v206, 4, v0
	v_mov_b32_e32 v22, v23
	v_mov_b32_e32 v21, v23
	v_mov_b32_e32 v20, v23
	s_and_saveexec_b64 s[8:9], s[6:7]
	s_cbranch_execz .LBB0_273
	v_add_u32_e32 v1, v206, v205
	s_movk_i32 s10, 0xffde
	s_waitcnt vmcnt(15)
	v_mad_u64_u32 v[2:3], s[10:11], v1, s10, v[116:117]
	v_cmp_lt_i32_e32 vcc, 7, v2
	s_and_saveexec_b64 s[10:11], vcc
	s_xor_b64 s[10:11], exec, s[10:11]
	s_cbranch_execz .LBB0_268
	v_cmp_lt_u32_e32 vcc, 15, v2
	s_and_saveexec_b64 s[12:13], vcc
	s_xor_b64 s[12:13], exec, s[12:13]
	s_cbranch_execz .LBB0_265
	v_cmp_lt_u32_e32 vcc, 23, v2
	s_and_saveexec_b64 s[14:15], vcc
	s_xor_b64 s[14:15], exec, s[14:15]
	s_cbranch_execz .LBB0_262
	v_cmp_lt_u32_e32 vcc, 31, v2
	v_lshlrev_b32_e32 v2, 3, v2
	s_and_saveexec_b64 s[18:19], vcc
	s_xor_b64 s[18:19], exec, s[18:19]
	v_add_u32_e32 v0, s40, v2
	s_andn2_saveexec_b64 s[18:19], s[18:19]
	v_add_u32_e32 v0, s41, v2
	s_or_b64 exec, exec, s[18:19]

.LBB0_1417:
	s_load_dwordx2 s[10:11], s[76:77], 0x0
	s_load_dwordx2 s[12:13], s[90:91], 0x0
	s_load_dwordx2 s[6:7], s[86:87], 0x0
	s_waitcnt vmcnt(0)
	v_or_b32_e32 v66, s63, v113
	v_add_u32_e32 v70, s29, v115
	s_cmp_gt_i32 s29, 0x3fff
	s_cselect_b32 s34, 0xffffc000, 0
	v_add_u32_e32 v70, s34, v70
	v_lshlrev_b32_e32 v66, 2, v66
	v_lshl_add_u32 v72, v70, 12, v66
	s_waitcnt lgkmcnt(0)
	s_cselect_b32 s4, s12, s10
	s_cselect_b32 s5, s13, s11
	s_cselect_b32 s8, s16, s6
	s_cselect_b32 s9, s17, s7
	s_cselect_b32 s34, s84, s82
	s_cselect_b32 s35, s85, s83
	global_load_dword v88, v66, s[34:35]
	global_load_dword v89, v66, s[34:35] offset:64
	global_load_dword v90, v66, s[34:35] offset:128
	global_load_dword v91, v66, s[34:35] offset:192
	global_load_dword v156, v72, s[4:5]
	global_load_dword v157, v72, s[4:5] offset:64
	global_load_dword v158, v72, s[4:5] offset:128
	global_load_dword v159, v72, s[4:5] offset:192
	v_add_u32_e32 v73, 0x1000, v72
	global_load_dword v160, v73, s[4:5]
	global_load_dword v161, v73, s[4:5] offset:64
	global_load_dword v162, v73, s[4:5] offset:128
	global_load_dword v163, v73, s[4:5] offset:192
	v_add_u32_e32 v74, 0x2000, v72
	global_load_dword v164, v74, s[4:5]
	global_load_dword v165, v74, s[4:5] offset:64
	global_load_dword v166, v74, s[4:5] offset:128
	global_load_dword v167, v74, s[4:5] offset:192
	v_add_u32_e32 v75, 0x3000, v72
	global_load_dword v168, v75, s[4:5]
	global_load_dword v169, v75, s[4:5] offset:64
	global_load_dword v170, v75, s[4:5] offset:128
	global_load_dword v171, v75, s[4:5] offset:192
	v_add_u32_e32 v76, 0x10000, v72
	global_load_dword v172, v76, s[4:5]
	global_load_dword v173, v76, s[4:5] offset:64
	global_load_dword v174, v76, s[4:5] offset:128
	global_load_dword v175, v76, s[4:5] offset:192
	v_add_u32_e32 v77, 0x11000, v72
	global_load_dword v176, v77, s[4:5]
	global_load_dword v177, v77, s[4:5] offset:64
	global_load_dword v178, v77, s[4:5] offset:128
	global_load_dword v179, v77, s[4:5] offset:192
	v_add_u32_e32 v78, 0x12000, v72
	global_load_dword v180, v78, s[4:5]
	global_load_dword v181, v78, s[4:5] offset:64
	global_load_dword v182, v78, s[4:5] offset:128
	global_load_dword v183, v78, s[4:5] offset:192
	v_add_u32_e32 v79, 0x13000, v72
	global_load_dword v184, v79, s[4:5]
	global_load_dword v185, v79, s[4:5] offset:64
	global_load_dword v186, v79, s[4:5] offset:128
	global_load_dword v187, v79, s[4:5] offset:192
	v_add_u32_e32 v80, 0x20000, v72
	global_load_dword v188, v80, s[4:5]
	global_load_dword v189, v80, s[4:5] offset:64
	global_load_dword v190, v80, s[4:5] offset:128
	global_load_dword v191, v80, s[4:5] offset:192
	v_add_u32_e32 v81, 0x21000, v72
	global_load_dword v192, v81, s[4:5]
	global_load_dword v193, v81, s[4:5] offset:64
	global_load_dword v194, v81, s[4:5] offset:128
	global_load_dword v195, v81, s[4:5] offset:192
	v_add_u32_e32 v82, 0x22000, v72
	global_load_dword v196, v82, s[4:5]
	global_load_dword v197, v82, s[4:5] offset:64
	global_load_dword v198, v82, s[4:5] offset:128
	global_load_dword v199, v82, s[4:5] offset:192
	v_add_u32_e32 v83, 0x23000, v72
	global_load_dword v200, v83, s[4:5]
	global_load_dword v201, v83, s[4:5] offset:64
	global_load_dword v202, v83, s[4:5] offset:128
	global_load_dword v203, v83, s[4:5] offset:192
	v_add_u32_e32 v84, 0x30000, v72
	global_load_dword v204, v84, s[4:5]
	global_load_dword v205, v84, s[4:5] offset:64
	global_load_dword v206, v84, s[4:5] offset:128
	global_load_dword v207, v84, s[4:5] offset:192
	v_add_u32_e32 v85, 0x31000, v72
	global_load_dword v212, v85, s[4:5]
	global_load_dword v213, v85, s[4:5] offset:64
	global_load_dword v214, v85, s[4:5] offset:128
	global_load_dword v215, v85, s[4:5] offset:192
	v_add_u32_e32 v86, 0x32000, v72
	global_load_dword v216, v86, s[4:5]
	global_load_dword v217, v86, s[4:5] offset:64
	global_load_dword v218, v86, s[4:5] offset:128
	global_load_dword v219, v86, s[4:5] offset:192
	v_add_u32_e32 v87, 0x33000, v72
	global_load_dword v220, v87, s[4:5]
	global_load_dword v221, v87, s[4:5] offset:64
	global_load_dword v222, v87, s[4:5] offset:128
	global_load_dword v223, v87, s[4:5] offset:192
	s_waitcnt vmcnt(0)
	v_fmac_f32_e32 v156, v62, v88
	v_fmac_f32_e32 v157, v58, v89
	v_fmac_f32_e32 v158, v54, v90
	v_fmac_f32_e32 v159, v50, v91
	v_fmac_f32_e32 v160, v63, v88
	v_fmac_f32_e32 v161, v59, v89
	v_fmac_f32_e32 v162, v55, v90
	v_fmac_f32_e32 v163, v51, v91
	v_fmac_f32_e32 v164, v64, v88
	v_fmac_f32_e32 v165, v60, v89
	v_fmac_f32_e32 v166, v56, v90
	v_fmac_f32_e32 v167, v52, v91
	v_fmac_f32_e32 v168, v65, v88
	v_fmac_f32_e32 v169, v61, v89
	v_fmac_f32_e32 v170, v57, v90
	v_fmac_f32_e32 v171, v53, v91
	v_fmac_f32_e32 v172, v46, v88
	v_fmac_f32_e32 v173, v42, v89
	v_fmac_f32_e32 v174, v38, v90
	v_fmac_f32_e32 v175, v34, v91
	v_fmac_f32_e32 v176, v47, v88
	v_fmac_f32_e32 v177, v43, v89
	v_fmac_f32_e32 v178, v39, v90
	v_fmac_f32_e32 v179, v35, v91
	v_fmac_f32_e32 v180, v48, v88
	v_fmac_f32_e32 v181, v44, v89
	v_fmac_f32_e32 v182, v40, v90
	v_fmac_f32_e32 v183, v36, v91
	v_fmac_f32_e32 v184, v49, v88
	v_fmac_f32_e32 v185, v45, v89
	v_fmac_f32_e32 v186, v41, v90
	v_fmac_f32_e32 v187, v37, v91
	v_fmac_f32_e32 v188, v30, v88
	v_fmac_f32_e32 v189, v26, v89
	v_fmac_f32_e32 v190, v22, v90
	v_fmac_f32_e32 v191, v18, v91
	v_fmac_f32_e32 v192, v31, v88
	v_fmac_f32_e32 v193, v27, v89
	v_fmac_f32_e32 v194, v23, v90
	v_fmac_f32_e32 v195, v19, v91
	v_fmac_f32_e32 v196, v32, v88
	v_fmac_f32_e32 v197, v28, v89
	v_fmac_f32_e32 v198, v24, v90
	v_fmac_f32_e32 v199, v20, v91
	v_fmac_f32_e32 v200, v33, v88
	v_fmac_f32_e32 v201, v29, v89
	v_fmac_f32_e32 v202, v25, v90
	v_fmac_f32_e32 v203, v21, v91
	v_fmac_f32_e32 v204, v12, v88
	v_fmac_f32_e32 v205, v8, v89
	v_fmac_f32_e32 v206, v4, v90
	v_fmac_f32_e32 v207, v0, v91
	v_fmac_f32_e32 v212, v13, v88
	v_fmac_f32_e32 v213, v9, v89
	v_fmac_f32_e32 v214, v5, v90
	v_fmac_f32_e32 v215, v1, v91
	v_fmac_f32_e32 v216, v14, v88
	v_fmac_f32_e32 v217, v10, v89
	v_fmac_f32_e32 v218, v6, v90
	v_fmac_f32_e32 v219, v2, v91
	v_fmac_f32_e32 v220, v15, v88
	v_fmac_f32_e32 v221, v11, v89
	v_fmac_f32_e32 v222, v7, v90
	v_fmac_f32_e32 v223, v3, v91
	global_store_dword v72, v156, s[8:9]
	global_store_dword v72, v157, s[8:9] offset:64
	global_store_dword v72, v158, s[8:9] offset:128
	global_store_dword v72, v159, s[8:9] offset:192
	global_store_dword v73, v160, s[8:9]
	global_store_dword v73, v161, s[8:9] offset:64
	global_store_dword v73, v162, s[8:9] offset:128
	global_store_dword v73, v163, s[8:9] offset:192
	global_store_dword v74, v164, s[8:9]
	global_store_dword v74, v165, s[8:9] offset:64
	global_store_dword v74, v166, s[8:9] offset:128
	global_store_dword v74, v167, s[8:9] offset:192
	global_store_dword v75, v168, s[8:9]
	global_store_dword v75, v169, s[8:9] offset:64
	global_store_dword v75, v170, s[8:9] offset:128
	global_store_dword v75, v171, s[8:9] offset:192
	global_store_dword v76, v172, s[8:9]
	global_store_dword v76, v173, s[8:9] offset:64
	global_store_dword v76, v174, s[8:9] offset:128
	global_store_dword v76, v175, s[8:9] offset:192
	global_store_dword v77, v176, s[8:9]
	global_store_dword v77, v177, s[8:9] offset:64
	global_store_dword v77, v178, s[8:9] offset:128
	global_store_dword v77, v179, s[8:9] offset:192
	global_store_dword v78, v180, s[8:9]
	global_store_dword v78, v181, s[8:9] offset:64
	global_store_dword v78, v182, s[8:9] offset:128
	global_store_dword v78, v183, s[8:9] offset:192
	global_store_dword v79, v184, s[8:9]
	global_store_dword v79, v185, s[8:9] offset:64
	global_store_dword v79, v186, s[8:9] offset:128
	global_store_dword v79, v187, s[8:9] offset:192
	global_store_dword v80, v188, s[8:9]
	global_store_dword v80, v189, s[8:9] offset:64
	global_store_dword v80, v190, s[8:9] offset:128
	global_store_dword v80, v191, s[8:9] offset:192
	global_store_dword v81, v192, s[8:9]
	global_store_dword v81, v193, s[8:9] offset:64
	global_store_dword v81, v194, s[8:9] offset:128
	global_store_dword v81, v195, s[8:9] offset:192
	global_store_dword v82, v196, s[8:9]
	global_store_dword v82, v197, s[8:9] offset:64
	global_store_dword v82, v198, s[8:9] offset:128
	global_store_dword v82, v199, s[8:9] offset:192
	global_store_dword v83, v200, s[8:9]
	global_store_dword v83, v201, s[8:9] offset:64
	global_store_dword v83, v202, s[8:9] offset:128
	global_store_dword v83, v203, s[8:9] offset:192
	global_store_dword v84, v204, s[8:9]
	global_store_dword v84, v205, s[8:9] offset:64
	global_store_dword v84, v206, s[8:9] offset:128
	global_store_dword v84, v207, s[8:9] offset:192
	global_store_dword v85, v212, s[8:9]
	global_store_dword v85, v213, s[8:9] offset:64
	global_store_dword v85, v214, s[8:9] offset:128
	global_store_dword v85, v215, s[8:9] offset:192
	global_store_dword v86, v216, s[8:9]
	global_store_dword v86, v217, s[8:9] offset:64
	global_store_dword v86, v218, s[8:9] offset:128
	global_store_dword v86, v219, s[8:9] offset:192
	global_store_dword v87, v220, s[8:9]
	global_store_dword v87, v221, s[8:9] offset:64
	global_store_dword v87, v222, s[8:9] offset:128
	global_store_dword v87, v223, s[8:9] offset:192
	s_mov_b64 s[4:5], exec
	s_branch .LBB0_1040
